# slc fast path gets its own copy of the post-QK tile tail reading scores straight from the MFMA result registers (30 v_mov per tile removed)
# speedup vs baseline: 1.0036x; 1.0036x over previous
; template <int MODE>
; DI void bias_init(f32x16& s0, f32x16& s1, const TP& tp, float fbm, int hi) {
; #pragma unroll
;     for (int r = 0; r < 16; ++r) {
;         const int kvc = 16 * (r >> 3) + (r & 7);
;         if (MODE == 0) { s0[r] = __builtin_fmaf(-L2E, tp.cs[kvc + 8 * hi], fbm); s1[r] = __builtin_fmaf(-L2E, tp.cs[kvc + 32 + 8 * hi], fbm); }
;         else { s0[r] = __builtin_fmaf(tp.sl, (float)kvc, fbm); s1[r] = __builtin_fmaf(tp.sl, (float)(kvc + 32), fbm); }
;     }
; }
; DI float max3_asm(float a, float b, float c) { float r; asm("v_max3_f32 %0, %1, %2, %3" : "=v"(r) : "v"(a), "v"(b), "v"(c)); return r; }
; template <bool MASK>
; DI float mask_rowmax(f32x16& s0, f32x16& s1, const TP& tp) {
;     if (MASK) {
; #pragma unroll
;         for (int r = 0; r < 16; ++r) {
;             const int kvc = 16 * (r >> 3) + (r & 7);
;             const bool v0 = tp.sel && (kvc <= tp.lim) && (kvc > tp.lim2), v1 = tp.sel && (kvc + 32 <= tp.lim) && (kvc + 32 > tp.lim2);
;             s0[r] = v0 ? s0[r] : -1e30f; s1[r] = v1 ? s1[r] : -1e30f;
;         }
;     }
;     const float seed = __builtin_fminf(s0[15], s1[15]);
;     float ma = seed, mb = seed;
; #pragma unroll
;     for (int r = 0; r < 16; r += 2) { ma = max3_asm(ma, s0[r], s1[r]); mb = max3_asm(mb, s0[r + 1], s1[r + 1]); }
;     const float mx = fmaxf(ma, mb);
;     return fmaxf(mx, __shfl_xor(mx, 32));
; }
; template <int MODE, bool MASK, bool WITH_O>
; DI void attn_tile_t(lptr Kt, lptr Vt, const bf16x8 (&qf)[4], f32x16& o0, f32x16& o1, RowState& rs, const TP& tp, int lane) {
;     const int hi = lane >> 5;
;     f32x16 s0, s1;
;     bias_init<MODE>(s0, s1, tp, tp.fb - rs.mref, hi);
;     qk_acc(Kt, qf, s0, s1, lane);
;     const float mx = mask_rowmax<MASK>(s0, s1, tp);
;     const bool was = rs.seen; rs.seen = was || (mx > -1e29f);
;     const bool trig = (mx > 8.f) || (!was && mx > -1e29f && mx < -8.f);
;     if (__builtin_expect(__any(trig), 0)) {
; DI void slc_unit(const Params& P, lptr L, int u, int tid, int lane, int wid) {
;     ...
;     ATT_LOOP_BEGIN(NTS, false, kb_ + (size_t)((int)list[jt] * 64) * PROJ_LD, vb_ + (size_t)((int)list[jt]) * 64, (const float*)nullptr)
;         const int j = (int)list[jt], kv0 = j * 64;
;         const bool sel = (sm[ql * 8 + (j >> 5)] >> (j & 31)) & 1u;
;         if (__any(sel)) {
.LBB0_613:
	s_add_i32 s1, s0, 0
	s_add_i32 s1, s1, 0x1a104
	v_mov_b32_e32 v0, s1
	ds_read_u8 v0, v0
	s_and_b32 s31, s0, 1
	s_waitcnt lgkmcnt(0)
	v_lshrrev_b32_e32 v34, 3, v0
	v_and_b32_e32 v34, 28, v34
	v_add_u32_e32 v34, v186, v34
	ds_read_b32 v34, v34
	v_and_b32_e32 v35, 31, v0
	s_waitcnt lgkmcnt(0)
	v_lshrrev_b32_e32 v36, v0, v34
	v_bfe_u32 v34, v34, v35, 1
	v_and_b32_e32 v35, 1, v36
	v_cmp_ne_u32_e32 vcc, 0, v34
	v_cmp_eq_u32_e64 s[28:29], 1, v35
	s_cbranch_vccz .LBB0_618
	v_lshl_or_b32 v0, v0, 6, v126
	v_sub_u32_e32 v34, v0, v91
	v_cvt_f32_i32_e32 v34, v34
	s_mov_b32 s0, 2.0
	v_sub_u32_e32 v152, v91, v0
	s_mov_b32 s1, 0x40400000
	v_cmp_lt_i32_e32 vcc, 54, v152
	v_fma_f32 v0, v150, v34, -v101
	s_cmp_eq_u64 vcc, exec
	s_cselect_b64 s[98:99], -1, 0
	s_orn2_b64 s[100:101], s[28:29], s[98:99]
	v_cndmask_b32_e64 v0, v210, v0, s[100:101]
	v_pk_fma_f32 v[36:37], v[94:95], s[0:1], v[0:1] op_sel_hi:[1,1,0]
	s_mov_b32 s0, 4.0
	s_mov_b32 s1, 0x40a00000
	v_pk_fma_f32 v[38:39], v[94:95], s[0:1], v[0:1] op_sel_hi:[1,1,0]
	s_mov_b32 s0, 0x40c00000
	s_mov_b32 s1, 0x40e00000
	v_pk_fma_f32 v[40:41], v[94:95], s[0:1], v[0:1] op_sel_hi:[1,1,0]
	s_mov_b32 s0, 0x41800000
	s_mov_b32 s1, 0x41880000
	v_pk_fma_f32 v[42:43], v[94:95], s[0:1], v[0:1] op_sel_hi:[1,1,0]
	s_mov_b32 s0, 0x41900000
	s_mov_b32 s1, 0x41980000
	v_pk_fma_f32 v[44:45], v[94:95], s[0:1], v[0:1] op_sel_hi:[1,1,0]
	s_mov_b32 s0, 0x41a00000
	s_mul_i32 s33, s31, 0x2400
	s_mov_b32 s1, 0x41a80000
	v_mov_b32_e32 v151, v150
	v_fma_f32 v34, 0, v150, v0
	v_add_f32_e32 v35, v150, v0
	v_pk_fma_f32 v[46:47], v[94:95], s[0:1], v[0:1] op_sel_hi:[1,1,0]
	v_pk_fma_f32 v[48:49], v[94:95], s[18:19], v[0:1] op_sel_hi:[1,1,0]
	v_pk_fma_f32 v[64:65], v[150:151], s[4:5], v[0:1] op_sel_hi:[1,1,0]
	v_pk_fma_f32 v[62:63], v[150:151], s[14:15], v[0:1] op_sel_hi:[1,1,0]
	v_pk_fma_f32 v[60:61], v[150:151], s[16:17], v[0:1] op_sel_hi:[1,1,0]
	v_pk_fma_f32 v[58:59], v[150:151], s[94:95], v[0:1] op_sel_hi:[1,1,0]
	v_pk_fma_f32 v[56:57], v[150:151], s[96:97], v[0:1] op_sel_hi:[1,1,0]
	v_pk_fma_f32 v[54:55], v[150:151], s[84:85], v[0:1] op_sel_hi:[1,1,0]
	v_pk_fma_f32 v[52:53], v[150:151], s[72:73], v[0:1] op_sel_hi:[1,1,0]
	v_pk_fma_f32 v[50:51], v[96:97], s[44:45], v[0:1] op_sel_hi:[1,1,0]
	v_add_u32_e32 v0, s33, v170
	ds_read_b128 v[102:105], v0 offset:4608
	ds_read_b128 v[106:109], v0
	ds_read_b128 v[110:113], v0 offset:32
	ds_read_b128 v[114:117], v0 offset:4640
	ds_read_b128 v[118:121], v0 offset:64
	ds_read_b128 v[158:161], v0 offset:4672
	ds_read_b128 v[162:165], v0 offset:96
	ds_read_b128 v[166:169], v0 offset:4704
	s_setprio 1
	s_waitcnt lgkmcnt(6)
	v_mfma_f32_32x32x16_bf16 v[34:49], v[106:109], v[66:69], v[34:49]
	v_mfma_f32_32x32x16_bf16 v[50:65], v[102:105], v[66:69], v[50:65]
	s_waitcnt lgkmcnt(5)
	v_mfma_f32_32x32x16_bf16 v[34:49], v[110:113], v[70:73], v[34:49]
	s_waitcnt lgkmcnt(4)
	v_mfma_f32_32x32x16_bf16 v[50:65], v[114:117], v[70:73], v[50:65]
	s_waitcnt lgkmcnt(3)
	v_mfma_f32_32x32x16_bf16 v[34:49], v[118:121], v[74:77], v[34:49]
	s_waitcnt lgkmcnt(2)
	v_mfma_f32_32x32x16_bf16 v[50:65], v[158:161], v[74:77], v[50:65]
	s_waitcnt lgkmcnt(1)
	v_mfma_f32_32x32x16_bf16 v[34:49], v[162:165], v[78:81], v[34:49]
	s_waitcnt lgkmcnt(0)
	v_mfma_f32_32x32x16_bf16 v[50:65], v[166:169], v[78:81], v[50:65]
	s_setprio 0
	s_and_b64 vcc, exec, s[98:99]
	s_cbranch_vccz .Lslc_masked
	s_nop 10
	v_max_f32_e32 v252, v65, v65
	v_max_f32_e32 v228, v49, v49
	v_min_f32_e32 v252, v228, v252
	v_max3_f32 v228, v252, v34, v50
	v_max3_f32 v252, v252, v35, v51
	s_mov_b32 s0, 0xefa18f08
	v_max3_f32 v228, v228, v36, v52
	v_max3_f32 v252, v252, v37, v53
	s_nop 0
	v_max3_f32 v228, v228, v38, v54
	v_max3_f32 v252, v252, v39, v55
	s_nop 0
	v_max3_f32 v228, v228, v40, v56
	v_max3_f32 v252, v252, v41, v57
	s_nop 0
	v_max3_f32 v228, v228, v42, v58
	v_max3_f32 v252, v252, v43, v59
	s_nop 0
	v_max3_f32 v228, v228, v44, v60
	v_max3_f32 v252, v252, v45, v61
	s_nop 0
	v_max3_f32 v228, v228, v46, v62
	v_max3_f32 v252, v252, v47, v63
	s_nop 0
	v_max3_f32 v228, v228, v48, v64
	v_max3_f32 v252, v252, v49, v65
	s_nop 0
	v_max_f32_e32 v252, v252, v252
	v_max_f32_e32 v228, v228, v228
	v_max_f32_e32 v252, v228, v252
	ds_bpermute_b32 v228, v149, v252
	s_waitcnt lgkmcnt(0)
	v_max_f32_e32 v228, v228, v228
	v_max_f32_e32 v252, v252, v228
	v_cmp_lt_f32_e64 s[28:29], s0, v252
	s_mov_b32 s0, 0x41000000
	v_cmp_nlt_f32_e32 vcc, s0, v252
	s_mov_b64 s[0:1], -1
	s_and_saveexec_b64 s[2:3], vcc
	s_mov_b32 s0, 0xc1000000
	v_cmp_gt_f32_e32 vcc, s0, v252
	s_xor_b64 s[0:1], s[22:23], -1
	s_and_b64 s[0:1], vcc, s[0:1]
	s_and_b64 s[0:1], s[28:29], s[0:1]
	s_orn2_b64 s[0:1], s[0:1], exec
	s_or_b64 exec, exec, s[2:3]
	v_cndmask_b32_e64 v228, 0, 1, s[0:1]
	v_cmp_ne_u32_e32 vcc, 0, v228
	s_cbranch_vccnz .Lsf_rare
; DI float exp2_fast(float x) { return __builtin_amdgcn_exp2f(x); }
; template <int MODE, bool MASK, bool WITH_O>
; DI void attn_tile_t(lptr Kt, lptr Vt, const bf16x8 (&qf)[4], f32x16& o0, f32x16& o1, RowState& rs, const TP& tp, int lane) {
;     ...
;     if (!WITH_O) {
;         float sum = 0.f;
; #pragma unroll
;         for (int r = 0; r < 16; ++r) { s0[r] = exp2_fast(s0[r]); s1[r] = exp2_fast(s1[r]); sum += s0[r] + s1[r]; }
;         rs.l += sum;
;     } else {
;         const int i = lane & 31;
;         lptr vp = Vt + i * KPB + hi * 16;
;         float sum = 0.f;
;     ...
;         PV_STEP(s0, 0, 0) PV_STEP(s0, 8, 32) PV_STEP(s1, 0, 64) PV_STEP(s1, 8, 96)
;     ...
;         rs.l += sum;
	v_exp_f32_e32 v252, v34
	v_exp_f32_e32 v103, v35
	v_exp_f32_e32 v111, v36
	v_exp_f32_e32 v105, v37
	v_add_f32_e32 v106, 0, v252
	v_add_f32_e32 v106, v103, v106
	v_add_f32_e32 v104, v111, v106
	v_exp_f32_e32 v106, v38
	v_exp_f32_e32 v107, v39
	v_add_u32_e32 v228, s33, v172
	v_exp_f32_e32 v108, v40
	ds_read_b128 v[236:239], v228 offset:18432
	ds_read_b128 v[240:243], v228 offset:23040
	v_add_f32_e32 v104, v105, v104
	v_exp_f32_e32 v109, v41
	v_add_f32_e32 v104, v106, v104
	v_add_f32_e32 v104, v107, v104
	v_add_f32_e32 v104, v108, v104
	v_add_f32_e32 v110, v109, v104
	v_cvt_pk_bf16_f32 v104, v252, v103
	v_cvt_pk_bf16_f32 v105, v111, v105
	v_cvt_pk_bf16_f32 v106, v106, v107
	v_cvt_pk_bf16_f32 v107, v108, v109
	s_or_b64 s[22:23], s[22:23], s[28:29]
	s_waitcnt lgkmcnt(1)
	v_mfma_f32_32x32x16_bf16 v[18:33], v[236:239], v[104:107], v[18:33]
	s_waitcnt lgkmcnt(0)
	v_mfma_f32_32x32x16_bf16 v[2:17], v[240:243], v[104:107], v[2:17]
	v_exp_f32_e32 v252, v42
	v_exp_f32_e32 v43, v43
	v_exp_f32_e32 v103, v44
	v_exp_f32_e32 v44, v45
	v_add_f32_e32 v229, v252, v110
	v_exp_f32_e32 v45, v46
	v_add_f32_e32 v229, v43, v229
	v_exp_f32_e32 v46, v47
	v_add_f32_e32 v42, v103, v229
	v_exp_f32_e32 v47, v48
	ds_read_b128 v[236:239], v228 offset:18464
	ds_read_b128 v[240:243], v228 offset:23072
	v_add_f32_e32 v42, v44, v42
	v_exp_f32_e32 v48, v49
	v_add_f32_e32 v42, v45, v42
	v_add_f32_e32 v42, v46, v42
	v_add_f32_e32 v42, v47, v42
	v_add_f32_e32 v229, v48, v42
	v_cvt_pk_bf16_f32 v42, v252, v43
	v_cvt_pk_bf16_f32 v43, v103, v44
	v_cvt_pk_bf16_f32 v44, v45, v46
	v_cvt_pk_bf16_f32 v45, v47, v48
	s_waitcnt lgkmcnt(1)
	s_nop 0
	v_mfma_f32_32x32x16_bf16 v[18:33], v[236:239], v[42:45], v[18:33]
	s_waitcnt lgkmcnt(0)
	v_mfma_f32_32x32x16_bf16 v[2:17], v[240:243], v[42:45], v[2:17]
	v_exp_f32_e32 v230, v50
	v_exp_f32_e32 v51, v51
	v_exp_f32_e32 v231, v52
	v_exp_f32_e32 v52, v53
	v_add_f32_e32 v229, v230, v229
	v_exp_f32_e32 v53, v54
	v_add_f32_e32 v229, v51, v229
	v_exp_f32_e32 v54, v55
	v_add_f32_e32 v50, v231, v229
	v_exp_f32_e32 v55, v56
	ds_read_b128 v[42:45], v228 offset:18496
	ds_read_b128 v[46:49], v228 offset:23104
	v_add_f32_e32 v50, v52, v50
	v_exp_f32_e32 v41, v57
	v_add_f32_e32 v50, v53, v50
	v_add_f32_e32 v50, v54, v50
	v_add_f32_e32 v50, v55, v50
	v_add_f32_e32 v56, v41, v50
	v_cvt_pk_bf16_f32 v50, v230, v51
	v_cvt_pk_bf16_f32 v51, v231, v52
	v_cvt_pk_bf16_f32 v52, v53, v54
	v_cvt_pk_bf16_f32 v53, v55, v41
	s_waitcnt lgkmcnt(1)
	s_nop 0
	v_mfma_f32_32x32x16_bf16 v[18:33], v[42:45], v[50:53], v[18:33]
	s_waitcnt lgkmcnt(0)
	v_mfma_f32_32x32x16_bf16 v[2:17], v[46:49], v[50:53], v[2:17]
	v_exp_f32_e32 v38, v58
	v_exp_f32_e32 v34, v59
	v_exp_f32_e32 v0, v60
	v_exp_f32_e32 v35, v61
	v_add_f32_e32 v41, v38, v56
	v_exp_f32_e32 v36, v62
	ds_read_b128 v[42:45], v228 offset:18528
	ds_read_b128 v[46:49], v228 offset:23136
	v_add_f32_e32 v41, v34, v41
	v_exp_f32_e32 v37, v63
	v_exp_f32_e32 v39, v64
	v_exp_f32_e32 v40, v65
	v_add_f32_e32 v41, v0, v41
	v_add_f32_e32 v41, v35, v41
	v_add_f32_e32 v41, v36, v41
	v_add_f32_e32 v41, v37, v41
	v_cvt_pk_bf16_f32 v34, v38, v34
	v_cvt_pk_bf16_f32 v35, v0, v35
	v_cvt_pk_bf16_f32 v36, v36, v37
	v_cvt_pk_bf16_f32 v37, v39, v40
	v_add_f32_e32 v41, v39, v41
	v_add_f32_e32 v41, v40, v41
	s_waitcnt lgkmcnt(1)
	v_mfma_f32_32x32x16_bf16 v[18:33], v[42:45], v[34:37], v[18:33]
	s_waitcnt lgkmcnt(0)
	v_mfma_f32_32x32x16_bf16 v[2:17], v[46:49], v[34:37], v[2:17]
	v_add_f32_e32 v100, v100, v41
	s_branch .LBB0_618
.Lsf_rare:
	v_mov_b32_e32 v106, v34
	v_mov_b32_e32 v102, v50
	v_mov_b32_e32 v103, v35
	v_mov_b32_e32 v104, v36
	v_mov_b32_e32 v50, v52
	v_mov_b32_e32 v105, v37
	v_mov_b32_e32 v52, v53
	v_mov_b32_e32 v107, v38
	v_mov_b32_e32 v53, v54
	v_mov_b32_e32 v108, v39
	v_mov_b32_e32 v54, v55
	v_mov_b32_e32 v109, v40
	v_mov_b32_e32 v55, v56
	v_mov_b32_e32 v110, v41
	v_mov_b32_e32 v41, v57
	v_mov_b32_e32 v56, v42
	v_mov_b32_e32 v38, v58
	v_mov_b32_e32 v34, v59
	v_mov_b32_e32 v42, v44
	v_mov_b32_e32 v0, v60
	v_mov_b32_e32 v44, v45
	v_mov_b32_e32 v35, v61
	v_mov_b32_e32 v45, v46
	v_mov_b32_e32 v36, v62
	v_mov_b32_e32 v46, v47
	v_mov_b32_e32 v37, v63
	v_mov_b32_e32 v47, v48
	v_mov_b32_e32 v39, v64
	v_mov_b32_e32 v48, v49
	v_mov_b32_e32 v40, v65
	v_mov_b32_e32 v49, v252
	s_branch .LBB0_622
